# PEER gather: per-token expert list ordered by a bucket sort (LDS atomics + wave prefix sum) instead of the 64-step compare-count sort; late ring refill
# baseline (speedup 1.0000x reference)
; DEV int ltid() { int t = threadIdx.x; asm volatile("" : "+v"(t)); return t; }
; DEV float bflo(unsigned u) { return __uint_as_float(u << 16); }
; DEV float bfhi(unsigned u) { return __uint_as_float(u & 0xffff0000u); }
; DEV void peer_gather_token(const Params& p, int tok) {
;   const int lane = ltid() & 63, b = tok >> 11;
;   float hx[32], acc[32];
;   {
;     const u16* hr = p.h + (size_t)tok * 2048 + lane * 32;
; #pragma unroll
;     for (int q = 0; q < 4; ++q) {
;       u32x4 v = *(const u32x4*)(hr + q * 8);
; #pragma unroll
;       for (int e = 0; e < 4; ++e) { hx[q * 8 + 2 * e] = bflo(v[e]); hx[q * 8 + 2 * e + 1] = bfhi(v[e]); }
;     }
;   }
; #pragma unroll
;   for (int e = 0; e < 32; ++e) acc[e] = 0.f;
;   const int e0 = p.eidx[(size_t)tok * 128 + lane], e1 = p.eidx[(size_t)tok * 128 + 64 + lane];
;   const int g0 = __builtin_bit_cast(int, p.gw[(size_t)tok * 128 + lane]), g1 = __builtin_bit_cast(int, p.gw[(size_t)tok * 128 + 64 + lane]);
;   u32x2 dn[4][3], up[4][3];
;   auto issue = [&](int k, int slot) {
;     const int e = (k < 64) ? __builtin_amdgcn_readlane(e0, k) : __builtin_amdgcn_readlane(e1, k - 64);
;     const unsigned char* dr = p.down8 + (size_t)e * ROW6 + lane * 24;
;     const unsigned char* ur = p.up8 + (size_t)e * ROW6 + lane * 24;
; #pragma unroll
;     for (int i = 0; i < 3; ++i) { dn[slot][i] = *(const u32x2*)(dr + i * 8); up[slot][i] = *(const u32x2*)(ur + i * 8); }
;   };
;   issue(0, 0); issue(1, 1); issue(2, 2);
.LBB0_1567:
	s_or_b64 exec, exec, s[0:1]
	s_waitcnt lgkmcnt(0)
	s_barrier
	s_mov_b64 exec, -1
	v_lshrrev_b32_e32 v2, 6, v0
	v_and_b32_e32 v3, 63, v0
	s_nop 0
	v_readfirstlane_b32 s38, v2
	s_add_i32 s20, s84, s38
	s_mov_b32 s90, s38
	s_lshl_b32 s21, s92, 2
	s_cmpk_lt_u32 s20, 0x4000
	s_cbranch_scc0 .Lp12_end
	v_lshlrev_b32_e32 v1, 4, v3
	v_lshlrev_b32_e32 v242, 2, v3
	v_lshlrev_b32_e32 v243, 3, v3
	v_lshlrev_b32_e32 v244, 4, v3
	v_add_u32_e32 v245, 0x1000, v244
	v_lshrrev_b32_e32 v2, 3, v3
	v_and_b32_e32 v246, 7, v3
	v_lshlrev_b32_e32 v2, 20, v2
	v_lshl_or_b32 v246, v246, 3, v2
	v_add_u32_e32 v247, 0x800000, v246
	v_add_u32_e32 v248, 0x1000000, v246
	v_add_u32_e32 v249, 0x1800000, v246
	v_add_u32_e32 v250, 0x2000000, v246
	v_add_u32_e32 v251, 0x2800000, v246
	v_add_u32_e32 v252, 0x3000000, v246
	v_add_u32_e32 v253, 0x3800000, v246
	v_mov_b32_e32 v212, 0x3c800000
	v_mov_b32_e32 v213, 0x3ba10414
	v_mov_b32_e32 v214, 0xb9c68948
	v_mov_b32_e32 v215, 0x7f800000
	v_mov_b32_e32 v207, 0
	s_mov_b32 s9, 0x378e98ab
	s_mov_b32 s10, 0x3b7cd369
	s_mov_b32 s11, 0xbcc618b2
	s_mov_b32 s12, 0x3dda74e4
	s_mov_b32 s13, 0x3f228afd
	s_mov_b32 s14, 0x3e03c728
	s_mov_b32 s15, 0xbfb8aa3b
	s_mov_b32 s16, 0x42ce8ed0
	s_mov_b32 s17, 0xc2b17218
	s_brev_b32 s18, -2
	s_mov_b32 s43, 1
	s_mov_b32 s19, 0
	s_lshl_b32 s38, s20, 9
	s_add_u32 s58, s66, s38
	s_addc_u32 s59, s67, 0
	global_load_dword v216, v242, s[58:59]
	global_load_dword v217, v242, s[58:59] offset:256
	s_add_u32 s58, s68, s38
	s_addc_u32 s59, s69, 0
	global_load_dword v218, v242, s[58:59]
	global_load_dword v219, v242, s[58:59] offset:256
	s_lshl_b32 s38, s20, 6
	s_add_u32 s58, s80, s38
	s_addc_u32 s59, s81, 0
	global_load_dwordx2 v[220:221], v246, s[58:59]
	global_load_dwordx2 v[222:223], v247, s[58:59]
	global_load_dwordx2 v[224:225], v248, s[58:59]
	global_load_dwordx2 v[226:227], v249, s[58:59]
	global_load_dwordx2 v[228:229], v250, s[58:59]
	global_load_dwordx2 v[230:231], v251, s[58:59]
	global_load_dwordx2 v[232:233], v252, s[58:59]
	global_load_dwordx2 v[234:235], v253, s[58:59]
	s_waitcnt vmcnt(0) lgkmcnt(0)
	s_mov_b32 s36, 0
	s_mov_b32 s37, 0
	v_and_b32_e32 v2, 63, v0
	v_lshrrev_b32_e32 v241, 6, v0
	v_lshlrev_b32_e32 v3, 9, v241
	v_add_u32_e32 v3, 0x1000, v3
	v_lshlrev_b32_e32 v241, 10, v241
	v_lshl_add_u32 v241, v2, 2, v241
	v_lshl_add_u32 v7, v2, 3, v3
	v_mov_b32_e32 v10, 0
	v_mov_b32_e32 v11, 0
	ds_write_b64 v7, v[10:11]
	v_lshrrev_b32_e32 v4, 7, v216
	v_lshrrev_b32_e32 v5, 7, v217
	v_lshl_add_u32 v4, v4, 2, v3
	v_lshl_add_u32 v5, v5, 2, v3
	v_mov_b32_e32 v6, 1
	s_waitcnt lgkmcnt(0)
	ds_add_rtn_u32 v239, v4, v6
	ds_add_rtn_u32 v240, v5, v6
	s_waitcnt lgkmcnt(0)
	ds_read_b64 v[10:11], v7
	s_waitcnt lgkmcnt(0)
	v_add_u32_e32 v8, v10, v11
	v_mov_b32_e32 v237, v8
	s_nop 1
	v_add_u32_dpp v237, v237, v237 row_shr:1 row_mask:0xf bank_mask:0xf bound_ctrl:1
	s_nop 1
	v_add_u32_dpp v237, v237, v237 row_shr:2 row_mask:0xf bank_mask:0xf bound_ctrl:1
	s_nop 1
	v_add_u32_dpp v237, v237, v237 row_shr:4 row_mask:0xf bank_mask:0xf bound_ctrl:1
	s_nop 1
	v_add_u32_dpp v237, v237, v237 row_shr:8 row_mask:0xf bank_mask:0xf bound_ctrl:1
	s_nop 1
	v_add_u32_dpp v237, v237, v237 row_bcast:15 row_mask:0xa bank_mask:0xf
	s_nop 1
	v_add_u32_dpp v237, v237, v237 row_bcast:31 row_mask:0xc bank_mask:0xf
	v_sub_u32_e32 v238, v237, v8
	v_add_u32_e32 v11, v238, v10
	v_mov_b32_e32 v10, v238
	ds_write_b64 v7, v[10:11]
	s_waitcnt lgkmcnt(0)
	ds_read_b32 v10, v4
	ds_read_b32 v11, v5
	s_waitcnt lgkmcnt(0)
	v_add_u32_e32 v239, v239, v10
	v_add_u32_e32 v240, v240, v11
	v_xor_b32_e32 v239, s19, v239
	v_xor_b32_e32 v240, s19, v240
	s_xor_b32 s19, s19, 0x7f
	v_and_b32_e32 v237, 0xfffffc00, v241
	v_lshl_add_u32 v239, v239, 2, v237
	v_lshl_add_u32 v240, v240, 2, v237
	ds_write_b32 v239, v216
	ds_write_b32 v240, v217
	ds_write_b32 v239, v218 offset:512
	ds_write_b32 v240, v219 offset:512
	s_waitcnt lgkmcnt(0)
	ds_read_b32 v216, v241
	ds_read_b32 v217, v241 offset:256
	ds_read_b32 v218, v241 offset:512
	ds_read_b32 v219, v241 offset:768
	s_waitcnt lgkmcnt(0)
	s_branch .Lp12_switch

; DEV float gelu_exact(float v) { return 0.5f * v * (1.f + erff(v * 0.7071067811865476f)); }
; DEV void peer_gather_token(const Params& p, int tok) {
;     ...
;   const int e0 = p.eidx[(size_t)tok * 128 + lane], e1 = p.eidx[(size_t)tok * 128 + 64 + lane];
;   const int g0 = __builtin_bit_cast(int, p.gw[(size_t)tok * 128 + lane]), g1 = __builtin_bit_cast(int, p.gw[(size_t)tok * 128 + 64 + lane]);
;   u32x2 dn[4][3], up[4][3];
;   auto issue = [&](int k, int slot) {
;     const int e = (k < 64) ? __builtin_amdgcn_readlane(e0, k) : __builtin_amdgcn_readlane(e1, k - 64);
;     const unsigned char* dr = p.down8 + (size_t)e * ROW6 + lane * 24;
;     const unsigned char* ur = p.up8 + (size_t)e * ROW6 + lane * 24;
; #pragma unroll
;     for (int i = 0; i < 3; ++i) { dn[slot][i] = *(const u32x2*)(dr + i * 8); up[slot][i] = *(const u32x2*)(ur + i * 8); }
;   };
;     ...
;       if (k + 3 < 128) issue(k + 3, (s + 3) & 3);
;       const v6u dq = v6u{dn[s][0][0], dn[s][0][1], dn[s][1][0], dn[s][1][1], dn[s][2][0], dn[s][2][1]};
;       const v32f dv = __builtin_amdgcn_cvt_scalef32_pk32_f32_fp6(dq, 1.0f);
;       float d0 = 0.f, d1 = 0.f, d2 = 0.f, d3 = 0.f;
; #pragma unroll
;       for (int i = 0; i < 8; ++i) { d0 += dv[4 * i] * hx[4 * i]; d1 += dv[4 * i + 1] * hx[4 * i + 1]; d2 += dv[4 * i + 2] * hx[4 * i + 2]; d3 += dv[4 * i + 3] * hx[4 * i + 3]; }
;       const float d = wave_sum_fast((d0 + d1) + (d2 + d3)) * (1.f / DOWN_SCALE);
;       const float gk = __builtin_bit_cast(float, (k < 64) ? __builtin_amdgcn_readlane(g0, k) : __builtin_amdgcn_readlane(g1, k - 64));
;       const float act = gelu_exact(d) * gk * (1.f / UP_SCALE);
;       const v6u uq = v6u{up[s][0][0], up[s][0][1], up[s][1][0], up[s][1][1], up[s][2][0], up[s][2][1]};
;       const v32f uv = __builtin_amdgcn_cvt_scalef32_pk32_f32_fp6(uq, 1.0f);
; #pragma unroll
;       for (int i = 0; i < 32; ++i) acc[i] += act * uv[i];
.Ljn_31:
	v_bfi_b32 v209, s18, v210, v205
	v_mul_f32_e32 v208, 0.5, v204
	v_add_f32_e32 v209, 1.0, v209
	v_mul_f32_e32 v208, v208, v209
	v_mul_f32_e32 v208, s26, v208
	v_mul_f32_e32 v206, 0x3e800000, v208
	v_pk_fma_f32 v[66:67], v[2:3], v[206:207], v[66:67] op_sel_hi:[1,0,1]
	v_pk_fma_f32 v[68:69], v[4:5], v[206:207], v[68:69] op_sel_hi:[1,0,1]
	v_pk_fma_f32 v[70:71], v[6:7], v[206:207], v[70:71] op_sel_hi:[1,0,1]
	v_pk_fma_f32 v[72:73], v[8:9], v[206:207], v[72:73] op_sel_hi:[1,0,1]
	v_pk_fma_f32 v[74:75], v[10:11], v[206:207], v[74:75] op_sel_hi:[1,0,1]
	v_pk_fma_f32 v[76:77], v[12:13], v[206:207], v[76:77] op_sel_hi:[1,0,1]
	v_pk_fma_f32 v[78:79], v[14:15], v[206:207], v[78:79] op_sel_hi:[1,0,1]
	v_pk_fma_f32 v[80:81], v[16:17], v[206:207], v[80:81] op_sel_hi:[1,0,1]
	v_pk_fma_f32 v[82:83], v[18:19], v[206:207], v[82:83] op_sel_hi:[1,0,1]
	v_pk_fma_f32 v[84:85], v[20:21], v[206:207], v[84:85] op_sel_hi:[1,0,1]
	v_pk_fma_f32 v[86:87], v[22:23], v[206:207], v[86:87] op_sel_hi:[1,0,1]
	v_pk_fma_f32 v[88:89], v[24:25], v[206:207], v[88:89] op_sel_hi:[1,0,1]
	v_pk_fma_f32 v[90:91], v[26:27], v[206:207], v[90:91] op_sel_hi:[1,0,1]
	v_pk_fma_f32 v[92:93], v[28:29], v[206:207], v[92:93] op_sel_hi:[1,0,1]
	v_pk_fma_f32 v[94:95], v[30:31], v[206:207], v[94:95] op_sel_hi:[1,0,1]
	v_pk_fma_f32 v[96:97], v[32:33], v[206:207], v[96:97] op_sel_hi:[1,0,1]
	s_mul_i32 s40, s25, 0xc00
	s_add_u32 s28, s62, s40
	s_addc_u32 s29, s63, 0
	global_load_dwordx4 v[182:185], v1, s[28:29]
	global_load_dwordx4 v[186:189], v1, s[28:29] offset:2048
	global_load_dwordx4 v[190:193], v1, s[28:29] offset:1024
	s_add_i32 s24, s24, 8
	s_and_b32 s24, s24, 63
	s_waitcnt vmcnt(21)
	v_and_b32_e32 v2, 63, v0
	v_lshrrev_b32_e32 v241, 6, v0
	v_lshlrev_b32_e32 v3, 9, v241
	v_add_u32_e32 v3, 0x1000, v3
	v_lshlrev_b32_e32 v241, 10, v241
	v_lshl_add_u32 v241, v2, 2, v241
	v_lshl_add_u32 v7, v2, 3, v3
	v_mov_b32_e32 v10, 0
	v_mov_b32_e32 v11, 0
	ds_write_b64 v7, v[10:11]
	v_lshrrev_b32_e32 v4, 7, v216
	v_lshrrev_b32_e32 v5, 7, v217
	v_lshl_add_u32 v4, v4, 2, v3
	v_lshl_add_u32 v5, v5, 2, v3
	v_mov_b32_e32 v6, 1
	s_waitcnt lgkmcnt(0)
	ds_add_rtn_u32 v239, v4, v6
	ds_add_rtn_u32 v240, v5, v6
	s_waitcnt lgkmcnt(0)
	ds_read_b64 v[10:11], v7
	s_waitcnt lgkmcnt(0)
	v_add_u32_e32 v8, v10, v11
	v_mov_b32_e32 v237, v8
	s_nop 1
	v_add_u32_dpp v237, v237, v237 row_shr:1 row_mask:0xf bank_mask:0xf bound_ctrl:1
	s_nop 1
	v_add_u32_dpp v237, v237, v237 row_shr:2 row_mask:0xf bank_mask:0xf bound_ctrl:1
	s_nop 1
	v_add_u32_dpp v237, v237, v237 row_shr:4 row_mask:0xf bank_mask:0xf bound_ctrl:1
	s_nop 1
	v_add_u32_dpp v237, v237, v237 row_shr:8 row_mask:0xf bank_mask:0xf bound_ctrl:1
	s_nop 1
	v_add_u32_dpp v237, v237, v237 row_bcast:15 row_mask:0xa bank_mask:0xf
	s_nop 1
	v_add_u32_dpp v237, v237, v237 row_bcast:31 row_mask:0xc bank_mask:0xf
	v_sub_u32_e32 v238, v237, v8
	v_add_u32_e32 v11, v238, v10
	v_mov_b32_e32 v10, v238
	ds_write_b64 v7, v[10:11]
	s_waitcnt lgkmcnt(0)
	ds_read_b32 v10, v4
	ds_read_b32 v11, v5
	s_waitcnt lgkmcnt(0)
	v_add_u32_e32 v239, v239, v10
	v_add_u32_e32 v240, v240, v11
	v_xor_b32_e32 v239, s19, v239
	v_xor_b32_e32 v240, s19, v240
	s_xor_b32 s19, s19, 0x7f
	v_and_b32_e32 v237, 0xfffffc00, v241
	v_lshl_add_u32 v239, v239, 2, v237
	v_lshl_add_u32 v240, v240, 2, v237
	ds_write_b32 v239, v216
	ds_write_b32 v240, v217
	ds_write_b32 v239, v218 offset:512
	ds_write_b32 v240, v219 offset:512
	s_waitcnt lgkmcnt(0)
	ds_read_b32 v216, v241
	ds_read_b32 v217, v241 offset:256
	ds_read_b32 v218, v241 offset:512
	ds_read_b32 v219, v241 offset:768
	s_waitcnt lgkmcnt(0)
	v_cvt_scalef32_pk32_f32_fp6 v[2:33], v[98:103], 1.0
	v_mul_f32_e32 v200, v2, v34
	v_mul_f32_e32 v201, v3, v35
	v_mul_f32_e32 v202, v4, v36
	v_mul_f32_e32 v203, v5, v37
	v_fmac_f32_e32 v200, v6, v38
	v_fmac_f32_e32 v201, v7, v39
	v_fmac_f32_e32 v202, v8, v40
	v_fmac_f32_e32 v203, v9, v41
	v_fmac_f32_e32 v200, v10, v42
	v_fmac_f32_e32 v201, v11, v43
	v_fmac_f32_e32 v202, v12, v44
	v_fmac_f32_e32 v203, v13, v45
	v_fmac_f32_e32 v200, v14, v46
	v_fmac_f32_e32 v201, v15, v47
	v_fmac_f32_e32 v202, v16, v48
	v_fmac_f32_e32 v203, v17, v49
	v_fmac_f32_e32 v200, v18, v50
	v_fmac_f32_e32 v201, v19, v51
	v_fmac_f32_e32 v202, v20, v52
	v_fmac_f32_e32 v203, v21, v53
	v_fmac_f32_e32 v200, v22, v54
	v_fmac_f32_e32 v201, v23, v55
	v_fmac_f32_e32 v202, v24, v56
	v_fmac_f32_e32 v203, v25, v57
	v_fmac_f32_e32 v200, v26, v58
	v_fmac_f32_e32 v201, v27, v59
	v_fmac_f32_e32 v202, v28, v60
	v_fmac_f32_e32 v203, v29, v61
	v_fmac_f32_e32 v200, v30, v62
	v_fmac_f32_e32 v201, v31, v63
	v_fmac_f32_e32 v202, v32, v64
	v_fmac_f32_e32 v203, v33, v65
	v_add_f32_e32 v200, v201, v200
	v_add_f32_e32 v202, v203, v202
	v_cvt_scalef32_pk32_f32_fp6 v[2:33], v[104:109], 1.0
	v_add_f32_e32 v200, v202, v200
	s_add_i32 s38, s24, 0
	v_readlane_b32 s26, v199, s38
	s_mov_b32 s39, 0
	v_readlane_b32 s25, v216, s39
	v_add_f32_dpp v200, v200, v200 quad_perm:[1,0,3,2] row_mask:0xf bank_mask:0xf bound_ctrl:1
	s_nop 1
	v_add_f32_dpp v200, v200, v200 quad_perm:[2,3,0,1] row_mask:0xf bank_mask:0xf bound_ctrl:1
	s_nop 1
	v_add_f32_dpp v200, v200, v200 row_half_mirror row_mask:0xf bank_mask:0xf bound_ctrl:1
	s_nop 1
	v_add_f32_dpp v200, v200, v200 row_mirror row_mask:0xf bank_mask:0xf bound_ctrl:1
	s_nop 1
	v_add_f32_dpp v200, v200, v200 row_bcast:15 row_mask:0xa bank_mask:0xf
	s_nop 1
	v_add_f32_dpp v200, v200, v200 row_bcast:31 row_mask:0xc bank_mask:0xf
	s_nop 0
	v_readlane_b32 s27, v200, 63
	v_mul_f32_e32 v204, s27, v212
	v_mul_f32_e32 v205, 0x3f3504f3, v204
	v_cmp_lt_f32_e64 s[32:33], |v205|, 1.0
	s_and_b64 vcc, exec, s[32:33]
	s_cbranch_vccnz .Lsm_33
	v_fma_f32 v208, |v205|, s9, v214
	v_fma_f32 v208, |v205|, v208, s10
	v_fma_f32 v208, |v205|, v208, s11
	v_fma_f32 v208, |v205|, v208, s12
	v_fma_f32 v208, |v205|, v208, s13
	v_fma_f32 v208, |v205|, v208, s14
	v_fma_f32 v208, |v205|, v208, |v205|
	v_mul_f32_e32 v209, 0xbfb8aa3b, v208
	v_fma_f32 v210, v208, s15, -v209
	v_rndne_f32_e32 v211, v209
	v_fmac_f32_e32 v210, 0xb2a5705f, v208
	v_sub_f32_e32 v209, v209, v211
	v_add_f32_e32 v209, v209, v210
	v_cvt_i32_f32_e32 v210, v211
	v_exp_f32_e32 v209, v209
	v_cmp_nlt_f32_e32 vcc, s16, v208
	v_ldexp_f32 v209, v209, v210
	s_nop 0
	v_cndmask_b32_e32 v209, 0, v209, vcc
	v_cmp_ngt_f32_e32 vcc, s17, v208
	s_nop 1
	v_cndmask_b32_e32 v208, v215, v209, vcc
	v_sub_f32_e32 v210, 1.0, v208
	s_branch .Ljn_33
